# v13 + windowed loops: second QK MFMA takes negm directly (no 16-reg copy); grid barrier: non-leader blocks poll the top generation word instead of the per-XCD one
# speedup vs baseline: 1.0191x; 1.0050x over previous
; DI unsigned xb_ld(unsigned* p) { return __hip_atomic_load(p, __ATOMIC_RELAXED, __HIP_MEMORY_SCOPE_AGENT); }
; DI unsigned xb_add(unsigned* p, unsigned v) { return __hip_atomic_fetch_add(p, v, __ATOMIC_RELAXED, __HIP_MEMORY_SCOPE_AGENT); }
; #define XB_SPIN(cond, bar) do { unsigned _sp = 0; while (cond) { __builtin_amdgcn_s_sleep(1); \
;     if ((++_sp & 255u) == 0u) { if (xb_ld(&(bar)[XB_TMO])) break; if (_sp > XB_SPIN_CAP) { atomicAdd(&(bar)[XB_TMO], 1u); break; } } } } while (0)
; DI void xcd_barrier(int wv, unsigned* bar0, volatile LAS unsigned* st) {
;     ...
;         const unsigned old = xb_add(&bar[XB_XSUB(x)], 1u);
;         const unsigned gen = old / nloc;
;         if (old + 1u == (gen + 1u) * nloc) {
;             __builtin_amdgcn_fence(__ATOMIC_RELEASE, "agent");
;             asm volatile("s_waitcnt vmcnt(0)" ::: "memory");
;             const unsigned og = xb_add(&bar[XB_TOP], 1u);
;             const unsigned tg = og / nx;
;             if (og + 1u == (tg + 1u) * nx) xb_add(&bar[XB_TOPGEN], 1u);
;             else XB_SPIN(xb_ld(&bar[XB_TOPGEN]) == tg, bar);
;             __builtin_amdgcn_fence(__ATOMIC_ACQUIRE, "agent");
;             xb_add(&bar[XB_XGEN(x)], 1u);
;             asm volatile("s_waitcnt vmcnt(0)" ::: "memory");
;         } else {
;             XB_SPIN(xb_ld(&bar[XB_XGEN(x)]) == gen, bar);
;             __builtin_amdgcn_fence(__ATOMIC_ACQUIRE, "agent");
;             asm volatile("s_waitcnt vmcnt(0)" ::: "memory");
;         }
.LBB0_622:
	s_lshl_b32 s0, s34, 8
	s_add_u32 s23, s54, s0
	s_addc_u32 s22, s55, 0
	v_mov_b32_e32 v1, s23
	v_add_co_u32_e32 v4, vcc, 0x1000, v1
	v_mov_b32_e32 v1, s22
	s_nop 0
	v_addc_co_u32_e32 v5, vcc, 0, v1, vcc
	v_mov_b32_e32 v1, 1
	flat_atomic_add v1, v[4:5], v1 offset:1024 sc0
	v_cvt_f32_u32_e32 v3, v2
	v_sub_u32_e32 v4, 0, v2
	v_rcp_iflag_f32_e32 v3, v3
	s_nop 0
	v_mul_f32_e32 v3, 0x4f7ffffe, v3
	v_cvt_u32_f32_e32 v3, v3
	v_mul_lo_u32 v4, v4, v3
	v_mul_hi_u32 v4, v3, v4
	v_add_u32_e32 v3, v3, v4
	s_waitcnt vmcnt(0) lgkmcnt(0)
	v_mul_hi_u32 v3, v1, v3
	v_mul_lo_u32 v5, v3, v2
	v_add_u32_e32 v4, 1, v1
	v_sub_u32_e32 v1, v1, v5
	v_add_u32_e32 v6, 1, v3
	v_sub_u32_e32 v5, v1, v2
	v_cmp_ge_u32_e32 vcc, v1, v2
	s_nop 1
	v_cndmask_b32_e32 v3, v3, v6, vcc
	v_cndmask_b32_e32 v1, v1, v5, vcc
	v_add_u32_e32 v5, 1, v3
	v_cmp_ge_u32_e32 vcc, v1, v2
	s_nop 1
	v_cndmask_b32_e32 v1, v3, v5, vcc
	v_mad_u64_u32 v[2:3], s[0:1], v2, v1, v[2:3]
	v_cmp_ne_u32_e32 vcc, v4, v2
	s_and_saveexec_b64 s[0:1], vcc
	s_xor_b64 s[0:1], exec, s[0:1]
	s_cbranch_execz .LBB0_635
	v_mov_b32_e32 v0, s54
	v_add_co_u32_e32 v2, vcc, 0x3000, v0
	v_mov_b32_e32 v0, s55
	s_nop 0
	v_addc_co_u32_e32 v3, vcc, 0, v0, vcc
	flat_load_dword v0, v[2:3] offset:1280 sc1
	s_add_u32 s6, s54, 0x3500
	s_addc_u32 s7, s55, 0
	s_waitcnt vmcnt(0) lgkmcnt(0)
	v_cmp_eq_u32_e32 vcc, v0, v1
	s_and_saveexec_b64 s[4:5], vcc
	s_cbranch_execz .LBB0_634
	s_mov_b32 s24, 1
	s_mov_b64 s[8:9], 0
	s_branch .LBB0_626

; DI unsigned xb_ld(unsigned* p) { return __hip_atomic_load(p, __ATOMIC_RELAXED, __HIP_MEMORY_SCOPE_AGENT); }
; DI unsigned xb_add(unsigned* p, unsigned v) { return __hip_atomic_fetch_add(p, v, __ATOMIC_RELAXED, __HIP_MEMORY_SCOPE_AGENT); }
; #define XB_SPIN(cond, bar) do { unsigned _sp = 0; while (cond) { __builtin_amdgcn_s_sleep(1); \
;     if ((++_sp & 255u) == 0u) { if (xb_ld(&(bar)[XB_TMO])) break; if (_sp > XB_SPIN_CAP) { atomicAdd(&(bar)[XB_TMO], 1u); break; } } } } while (0)
; DI void xcd_barrier(int wv, unsigned* bar0, volatile LAS unsigned* st) {
;     ...
;         const unsigned old = xb_add(&bar[XB_XSUB(x)], 1u);
;         const unsigned gen = old / nloc;
;         if (old + 1u == (gen + 1u) * nloc) {
;             __builtin_amdgcn_fence(__ATOMIC_RELEASE, "agent");
;             asm volatile("s_waitcnt vmcnt(0)" ::: "memory");
;             const unsigned og = xb_add(&bar[XB_TOP], 1u);
;             const unsigned tg = og / nx;
;             if (og + 1u == (tg + 1u) * nx) xb_add(&bar[XB_TOPGEN], 1u);
;             else XB_SPIN(xb_ld(&bar[XB_TOPGEN]) == tg, bar);
;             __builtin_amdgcn_fence(__ATOMIC_ACQUIRE, "agent");
;             xb_add(&bar[XB_XGEN(x)], 1u);
;             asm volatile("s_waitcnt vmcnt(0)" ::: "memory");
;         } else {
;             XB_SPIN(xb_ld(&bar[XB_XGEN(x)]) == gen, bar);
;             __builtin_amdgcn_fence(__ATOMIC_ACQUIRE, "agent");
;             asm volatile("s_waitcnt vmcnt(0)" ::: "memory");
;         }
.LBB0_886:
	s_lshl_b32 s0, s34, 8
	s_add_u32 s23, s64, s0
	s_addc_u32 s22, s65, 0
	v_mov_b32_e32 v1, s23
	v_add_co_u32_e32 v4, vcc, 0x1000, v1
	v_mov_b32_e32 v1, s22
	s_nop 0
	v_addc_co_u32_e32 v5, vcc, 0, v1, vcc
	v_mov_b32_e32 v1, 1
	flat_atomic_add v3, v[4:5], v1 offset:1024 sc0
	v_cvt_f32_u32_e32 v1, v2
	v_sub_u32_e32 v4, 0, v2
	v_rcp_iflag_f32_e32 v1, v1
	s_nop 0
	v_mul_f32_e32 v1, 0x4f7ffffe, v1
	v_cvt_u32_f32_e32 v1, v1
	v_mul_lo_u32 v4, v4, v1
	v_mul_hi_u32 v4, v1, v4
	v_add_u32_e32 v1, v1, v4
	s_waitcnt vmcnt(0) lgkmcnt(0)
	v_mul_hi_u32 v1, v3, v1
	v_mul_lo_u32 v4, v1, v2
	v_sub_u32_e32 v4, v3, v4
	v_cmp_ge_u32_e32 vcc, v4, v2
	v_add_u32_e32 v5, 1, v1
	s_nop 0
	v_cndmask_b32_e32 v1, v1, v5, vcc
	v_sub_u32_e32 v5, v4, v2
	v_cndmask_b32_e32 v4, v4, v5, vcc
	v_cmp_ge_u32_e32 vcc, v4, v2
	v_add_u32_e32 v4, 1, v1
	s_nop 0
	v_cndmask_b32_e32 v1, v1, v4, vcc
	v_add_u32_e32 v4, 1, v3
	v_mad_u64_u32 v[2:3], s[0:1], v2, v1, v[2:3]
	v_cmp_ne_u32_e32 vcc, v4, v2
	s_and_saveexec_b64 s[0:1], vcc
	s_xor_b64 s[0:1], exec, s[0:1]
	s_cbranch_execz .LBB0_899
	v_mov_b32_e32 v0, s64
	v_add_co_u32_e32 v2, vcc, 0x3000, v0
	v_mov_b32_e32 v0, s65
	s_nop 0
	v_addc_co_u32_e32 v3, vcc, 0, v0, vcc
	flat_load_dword v0, v[2:3] offset:1280 sc1
	s_add_u32 s6, s64, 0x3500
	s_addc_u32 s7, s65, 0
	s_waitcnt vmcnt(0) lgkmcnt(0)
	v_cmp_eq_u32_e32 vcc, v0, v1
	s_and_saveexec_b64 s[4:5], vcc
	s_cbranch_execz .LBB0_898
	s_mov_b32 s24, 1
	s_mov_b64 s[8:9], 0
	s_branch .LBB0_890

; template <int DQK, bool WIN>
; DI void attn_run(int wv, const bf16_t* Qrow0, int qs, const bf16_t* Kb, int ks, const bf16_t* Vb, int vs,
;                  int kt0, int kt1, int qpos0, int window, LAS unsigned char* lds, f32x16 (&o)[2], float& m_out, float& l_out) {
;     ...
;             f32x16 p0 = __builtin_amdgcn_mfma_f32_32x32x16_bf16(kf0[0], q[0], negm, 0, 0, 0);
;             f32x16 p1 = __builtin_amdgcn_mfma_f32_32x32x16_bf16(kf1[0], q[0], negm, 0, 0, 0);
; #pragma unroll
;             for (int ds = 1; ds < NDS; ++ds) {
;                 p0 = __builtin_amdgcn_mfma_f32_32x32x16_bf16(kf0[ds], q[ds], p0, 0, 0, 0);
;                 p1 = __builtin_amdgcn_mfma_f32_32x32x16_bf16(kf1[ds], q[ds], p1, 0, 0, 0);
;             }
.LBB0_1246:
	s_add_i32 s26, s44, s13
	s_sub_i32 vcc_hi, s26, 64
	s_add_i32 m0, s34, 31
	s_cmp_ge_i32 vcc_hi, m0
	s_cselect_b32 m0, 1, 0
	s_sub_i32 vcc_lo, s35, 0x5e
	s_cmp_le_i32 vcc_hi, vcc_lo
	s_cselect_b32 vcc_lo, 1, 0
	s_and_b32 m0, m0, vcc_lo
	s_and_b32 s15, s12, 1
	s_sub_i32 s28, s26, 64
	s_add_i32 s26, s26, -1
	s_cmp_ge_i32 s26, s34
	s_cselect_b64 s[26:27], -1, 0
	s_cmp_le_i32 s28, s35
	s_cselect_b64 s[28:29], -1, 0
	s_and_b64 s[26:27], s[26:27], s[28:29]
	s_andn2_b64 vcc, exec, s[26:27]
	s_cbranch_vccnz .LBB0_1255
	s_mul_i32 s26, s15, 0x5400
	s_add_i32 s28, s26, 0
	v_add3_u32 v52, s28, v154, v144
	ds_read_b128 v[48:51], v52
	ds_read_b128 v[112:115], v52 offset:32
	ds_read_b128 v[116:119], v52 offset:4608
	ds_read_b128 v[120:123], v52 offset:4640
	ds_read_b128 v[124:127], v52 offset:64
	ds_read_b128 v[146:149], v52 offset:96
	ds_read_b128 v[162:165], v52 offset:4672
	ds_read_b128 v[166:169], v52 offset:4704
	s_xor_b64 s[26:27], s[24:25], -1
	s_setprio 1
	s_waitcnt lgkmcnt(0)
	v_mfma_f32_32x32x16_bf16 v[64:79], v[48:51], v[80:83], v[32:47]
	s_waitcnt lgkmcnt(5)
	v_mfma_f32_32x32x16_bf16 v[48:63], v[116:119], v[80:83], v[32:47]
	s_setprio 0
	v_mfma_f32_32x32x16_bf16 v[64:79], v[112:115], v[84:87], v[64:79]
	v_add_u32_e32 v112, s28, v156
	s_waitcnt lgkmcnt(4)
	v_mfma_f32_32x32x16_bf16 v[48:63], v[120:123], v[84:87], v[48:63]
	v_add3_u32 v152, v112, v155, v157
	ds_read_b64_tr_b16 v[132:133], v152 offset:9216
	ds_read_b64_tr_b16 v[134:135], v152 offset:10752
	ds_read_b64_tr_b16 v[130:131], v152 offset:10816
	ds_read_b64_tr_b16 v[128:129], v152 offset:9280
	s_waitcnt lgkmcnt(7)
	v_mfma_f32_32x32x16_bf16 v[64:79], v[124:127], v[88:91], v[64:79]
	ds_read_b64_tr_b16 v[124:125], v152 offset:12288
	ds_read_b64_tr_b16 v[126:127], v152 offset:13824
	ds_read_b64_tr_b16 v[122:123], v152 offset:13888
	ds_read_b64_tr_b16 v[120:121], v152 offset:12352
	ds_read_b64_tr_b16 v[116:117], v152 offset:15360
	ds_read_b64_tr_b16 v[118:119], v152 offset:16896
	ds_read_b64_tr_b16 v[114:115], v152 offset:16960
	ds_read_b64_tr_b16 v[112:113], v152 offset:15424
	s_waitcnt lgkmcnt(13)
	v_mfma_f32_32x32x16_bf16 v[48:63], v[162:165], v[88:91], v[48:63]
	v_mfma_f32_32x32x16_bf16 v[64:79], v[146:149], v[92:95], v[64:79]
	s_waitcnt lgkmcnt(12)
	v_mfma_f32_32x32x16_bf16 v[48:63], v[166:169], v[92:95], v[48:63]
	s_cmp_eq_u32 m0, 1
	s_cbranch_scc0 .Lwd_slow
	s_nop 7
	v_mov_b32_e32 v142, v64
	s_nop 0
	v_mov_b32_e32 v64, v48
	v_mov_b32_e32 v143, v65
	v_mov_b32_e32 v65, v49
	v_mov_b32_e32 v146, v66
	v_mov_b32_e32 v66, v50
	v_mov_b32_e32 v147, v67
	v_mov_b32_e32 v67, v51
	v_mov_b32_e32 v148, v68
	v_mov_b32_e32 v68, v52
	v_mov_b32_e32 v149, v69
	v_mov_b32_e32 v69, v53
	v_mov_b32_e32 v150, v70
	v_mov_b32_e32 v70, v54
	v_mov_b32_e32 v151, v71
	v_mov_b32_e32 v71, v55
	s_branch .Lwd_join

; template <int DQK, bool WIN>
; DI void attn_run(int wv, const bf16_t* Qrow0, int qs, const bf16_t* Kb, int ks, const bf16_t* Vb, int vs,
;                  int kt0, int kt1, int qpos0, int window, LAS unsigned char* lds, f32x16 (&o)[2], float& m_out, float& l_out) {
;     ...
;             f32x16 p0 = __builtin_amdgcn_mfma_f32_32x32x16_bf16(kf0[0], q[0], negm, 0, 0, 0);
;             f32x16 p1 = __builtin_amdgcn_mfma_f32_32x32x16_bf16(kf1[0], q[0], negm, 0, 0, 0);
; #pragma unroll
;             for (int ds = 1; ds < NDS; ++ds) {
;                 p0 = __builtin_amdgcn_mfma_f32_32x32x16_bf16(kf0[ds], q[ds], p0, 0, 0, 0);
;                 p1 = __builtin_amdgcn_mfma_f32_32x32x16_bf16(kf1[ds], q[ds], p1, 0, 0, 0);
;             }
.LBB0_1272:
	s_add_i32 s15, s68, -2
	s_add_i32 s36, s12, s13
	s_add_i32 m0, s75, 31
	s_cmp_ge_i32 s36, m0
	s_cselect_b32 m0, 1, 0
	s_sub_i32 vcc_lo, s14, 0x5e
	s_cmp_le_i32 s36, vcc_lo
	s_cselect_b32 vcc_lo, 1, 0
	s_and_b32 m0, m0, vcc_lo
	s_and_b32 s15, s15, 1
	s_add_i32 s30, s36, 63
	s_cmp_ge_i32 s30, s75
	s_cselect_b64 s[30:31], -1, 0
	s_cmp_le_u32 s36, s14
	s_cselect_b64 s[36:37], -1, 0
	s_and_b64 s[30:31], s[30:31], s[36:37]
	s_andn2_b64 vcc, exec, s[30:31]
	s_cbranch_vccnz .LBB0_1281
	s_mul_i32 s30, s15, 0x5400
	s_add_i32 s36, s30, 0
	v_add3_u32 v52, s36, v154, v144
	ds_read_b128 v[48:51], v52
	ds_read_b128 v[112:115], v52 offset:32
	ds_read_b128 v[116:119], v52 offset:4608
	ds_read_b128 v[120:123], v52 offset:4640
	ds_read_b128 v[124:127], v52 offset:64
	ds_read_b128 v[146:149], v52 offset:96
	ds_read_b128 v[162:165], v52 offset:4672
	ds_read_b128 v[166:169], v52 offset:4704
	s_xor_b64 s[30:31], s[28:29], -1
	s_setprio 1
	s_waitcnt lgkmcnt(0)
	v_mfma_f32_32x32x16_bf16 v[64:79], v[48:51], v[80:83], v[32:47]
	v_mfma_f32_32x32x16_bf16 v[48:63], v[116:119], v[80:83], v[32:47]
	s_setprio 0
	v_mfma_f32_32x32x16_bf16 v[64:79], v[112:115], v[84:87], v[64:79]
	v_add_u32_e32 v112, s36, v156
	v_add3_u32 v152, v112, v155, v157
	v_mfma_f32_32x32x16_bf16 v[48:63], v[120:123], v[84:87], v[48:63]
	v_mfma_f32_32x32x16_bf16 v[64:79], v[124:127], v[88:91], v[64:79]
	ds_read_b64_tr_b16 v[132:133], v152 offset:9216
	ds_read_b64_tr_b16 v[134:135], v152 offset:10752
	ds_read_b64_tr_b16 v[130:131], v152 offset:10816
	ds_read_b64_tr_b16 v[128:129], v152 offset:9280
	ds_read_b64_tr_b16 v[124:125], v152 offset:12288
	ds_read_b64_tr_b16 v[126:127], v152 offset:13824
	ds_read_b64_tr_b16 v[122:123], v152 offset:13888
	ds_read_b64_tr_b16 v[120:121], v152 offset:12352
	ds_read_b64_tr_b16 v[116:117], v152 offset:15360
	ds_read_b64_tr_b16 v[118:119], v152 offset:16896
	ds_read_b64_tr_b16 v[114:115], v152 offset:16960
	ds_read_b64_tr_b16 v[112:113], v152 offset:15424
	v_mfma_f32_32x32x16_bf16 v[48:63], v[162:165], v[88:91], v[48:63]
	v_mfma_f32_32x32x16_bf16 v[64:79], v[146:149], v[92:95], v[64:79]
	v_mfma_f32_32x32x16_bf16 v[48:63], v[166:169], v[92:95], v[48:63]
	s_cmp_eq_u32 m0, 1
	s_cbranch_scc0 .Lwc_slow
	s_nop 8
	v_mov_b32_e32 v142, v64
	v_mov_b32_e32 v64, v48
	v_mov_b32_e32 v143, v65
	v_mov_b32_e32 v65, v49
	v_mov_b32_e32 v146, v66
	v_mov_b32_e32 v66, v50
	v_mov_b32_e32 v147, v67
	v_mov_b32_e32 v67, v51
	v_mov_b32_e32 v148, v68
	v_mov_b32_e32 v68, v52
	v_mov_b32_e32 v149, v69
	v_mov_b32_e32 v69, v53
	v_mov_b32_e32 v150, v70
	v_mov_b32_e32 v70, v54
	v_mov_b32_e32 v151, v71
	v_mov_b32_e32 v71, v55
	s_branch .Lwc_join

; DI unsigned xb_ld(unsigned* p) { return __hip_atomic_load(p, __ATOMIC_RELAXED, __HIP_MEMORY_SCOPE_AGENT); }
; DI unsigned xb_add(unsigned* p, unsigned v) { return __hip_atomic_fetch_add(p, v, __ATOMIC_RELAXED, __HIP_MEMORY_SCOPE_AGENT); }
; #define XB_SPIN(cond, bar) do { unsigned _sp = 0; while (cond) { __builtin_amdgcn_s_sleep(1); \
;     if ((++_sp & 255u) == 0u) { if (xb_ld(&(bar)[XB_TMO])) break; if (_sp > XB_SPIN_CAP) { atomicAdd(&(bar)[XB_TMO], 1u); break; } } } } while (0)
; DI void xcd_barrier(int wv, unsigned* bar0, volatile LAS unsigned* st) {
;     ...
;         const unsigned old = xb_add(&bar[XB_XSUB(x)], 1u);
;         const unsigned gen = old / nloc;
;         if (old + 1u == (gen + 1u) * nloc) {
;             __builtin_amdgcn_fence(__ATOMIC_RELEASE, "agent");
;             asm volatile("s_waitcnt vmcnt(0)" ::: "memory");
;             const unsigned og = xb_add(&bar[XB_TOP], 1u);
;             const unsigned tg = og / nx;
;             if (og + 1u == (tg + 1u) * nx) xb_add(&bar[XB_TOPGEN], 1u);
;             else XB_SPIN(xb_ld(&bar[XB_TOPGEN]) == tg, bar);
;             __builtin_amdgcn_fence(__ATOMIC_ACQUIRE, "agent");
;             xb_add(&bar[XB_XGEN(x)], 1u);
;             asm volatile("s_waitcnt vmcnt(0)" ::: "memory");
;         } else {
;             XB_SPIN(xb_ld(&bar[XB_XGEN(x)]) == gen, bar);
;             __builtin_amdgcn_fence(__ATOMIC_ACQUIRE, "agent");
;             asm volatile("s_waitcnt vmcnt(0)" ::: "memory");
;         }
.LBB0_1454:
	s_lshl_b32 s0, s34, 8
	s_add_u32 s23, s74, s0
	s_addc_u32 s22, s75, 0
	v_mov_b32_e32 v1, s23
	v_add_co_u32_e32 v4, vcc, 0x1000, v1
	v_mov_b32_e32 v1, s22
	s_nop 0
	v_addc_co_u32_e32 v5, vcc, 0, v1, vcc
	v_mov_b32_e32 v1, 1
	flat_atomic_add v3, v[4:5], v1 offset:1024 sc0
	v_cvt_f32_u32_e32 v1, v2
	v_sub_u32_e32 v4, 0, v2
	v_rcp_iflag_f32_e32 v1, v1
	s_nop 0
	v_mul_f32_e32 v1, 0x4f7ffffe, v1
	v_cvt_u32_f32_e32 v1, v1
	v_mul_lo_u32 v4, v4, v1
	v_mul_hi_u32 v4, v1, v4
	v_add_u32_e32 v1, v1, v4
	s_waitcnt vmcnt(0) lgkmcnt(0)
	v_mul_hi_u32 v1, v3, v1
	v_mul_lo_u32 v4, v1, v2
	v_sub_u32_e32 v4, v3, v4
	v_cmp_ge_u32_e32 vcc, v4, v2
	v_add_u32_e32 v5, 1, v1
	s_nop 0
	v_cndmask_b32_e32 v1, v1, v5, vcc
	v_sub_u32_e32 v5, v4, v2
	v_cndmask_b32_e32 v4, v4, v5, vcc
	v_cmp_ge_u32_e32 vcc, v4, v2
	v_add_u32_e32 v4, 1, v1
	s_nop 0
	v_cndmask_b32_e32 v1, v1, v4, vcc
	v_add_u32_e32 v4, 1, v3
	v_mad_u64_u32 v[2:3], s[0:1], v2, v1, v[2:3]
	v_cmp_ne_u32_e32 vcc, v4, v2
	s_and_saveexec_b64 s[0:1], vcc
	s_xor_b64 s[0:1], exec, s[0:1]
	s_cbranch_execz .LBB0_1467
	v_mov_b32_e32 v0, s74
	v_add_co_u32_e32 v2, vcc, 0x3000, v0
	v_mov_b32_e32 v0, s75
	s_nop 0
	v_addc_co_u32_e32 v3, vcc, 0, v0, vcc
	flat_load_dword v0, v[2:3] offset:1280 sc1
	s_add_u32 s6, s74, 0x3500
	s_addc_u32 s7, s75, 0
	s_waitcnt vmcnt(0) lgkmcnt(0)
	v_cmp_eq_u32_e32 vcc, v0, v1
	s_and_saveexec_b64 s[4:5], vcc
	s_cbranch_execz .LBB0_1466
	s_mov_b32 s24, 1
	s_mov_b64 s[8:9], 0
	s_branch .LBB0_1458

; DI unsigned xb_ld(unsigned* p) { return __hip_atomic_load(p, __ATOMIC_RELAXED, __HIP_MEMORY_SCOPE_AGENT); }
; DI unsigned xb_add(unsigned* p, unsigned v) { return __hip_atomic_fetch_add(p, v, __ATOMIC_RELAXED, __HIP_MEMORY_SCOPE_AGENT); }
; #define XB_SPIN(cond, bar) do { unsigned _sp = 0; while (cond) { __builtin_amdgcn_s_sleep(1); \
;     if ((++_sp & 255u) == 0u) { if (xb_ld(&(bar)[XB_TMO])) break; if (_sp > XB_SPIN_CAP) { atomicAdd(&(bar)[XB_TMO], 1u); break; } } } } while (0)
; DI void xcd_barrier(int wv, unsigned* bar0, volatile LAS unsigned* st) {
;     ...
;         const unsigned old = xb_add(&bar[XB_XSUB(x)], 1u);
;         const unsigned gen = old / nloc;
;         if (old + 1u == (gen + 1u) * nloc) {
;             __builtin_amdgcn_fence(__ATOMIC_RELEASE, "agent");
;             asm volatile("s_waitcnt vmcnt(0)" ::: "memory");
;             const unsigned og = xb_add(&bar[XB_TOP], 1u);
;             const unsigned tg = og / nx;
;             if (og + 1u == (tg + 1u) * nx) xb_add(&bar[XB_TOPGEN], 1u);
;             else XB_SPIN(xb_ld(&bar[XB_TOPGEN]) == tg, bar);
;             __builtin_amdgcn_fence(__ATOMIC_ACQUIRE, "agent");
;             xb_add(&bar[XB_XGEN(x)], 1u);
;             asm volatile("s_waitcnt vmcnt(0)" ::: "memory");
;         } else {
;             XB_SPIN(xb_ld(&bar[XB_XGEN(x)]) == gen, bar);
;             __builtin_amdgcn_fence(__ATOMIC_ACQUIRE, "agent");
;             asm volatile("s_waitcnt vmcnt(0)" ::: "memory");
;         }
.LBB0_1534:
	s_lshl_b32 s0, s35, 8
	s_add_u32 s23, s74, s0
	s_addc_u32 s22, s75, 0
	v_mov_b32_e32 v1, s23
	v_add_co_u32_e32 v4, vcc, 0x1000, v1
	v_mov_b32_e32 v1, s22
	s_nop 0
	v_addc_co_u32_e32 v5, vcc, 0, v1, vcc
	v_mov_b32_e32 v1, 1
	flat_atomic_add v3, v[4:5], v1 offset:1024 sc0
	v_cvt_f32_u32_e32 v1, v2
	v_sub_u32_e32 v4, 0, v2
	v_rcp_iflag_f32_e32 v1, v1
	s_nop 0
	v_mul_f32_e32 v1, 0x4f7ffffe, v1
	v_cvt_u32_f32_e32 v1, v1
	v_mul_lo_u32 v4, v4, v1
	v_mul_hi_u32 v4, v1, v4
	v_add_u32_e32 v1, v1, v4
	s_waitcnt vmcnt(0) lgkmcnt(0)
	v_mul_hi_u32 v1, v3, v1
	v_mul_lo_u32 v4, v1, v2
	v_sub_u32_e32 v4, v3, v4
	v_cmp_ge_u32_e32 vcc, v4, v2
	v_add_u32_e32 v5, 1, v1
	s_nop 0
	v_cndmask_b32_e32 v1, v1, v5, vcc
	v_sub_u32_e32 v5, v4, v2
	v_cndmask_b32_e32 v4, v4, v5, vcc
	v_cmp_ge_u32_e32 vcc, v4, v2
	v_add_u32_e32 v4, 1, v1
	s_nop 0
	v_cndmask_b32_e32 v1, v1, v4, vcc
	v_add_u32_e32 v4, 1, v3
	v_mad_u64_u32 v[2:3], s[0:1], v2, v1, v[2:3]
	v_cmp_ne_u32_e32 vcc, v4, v2
	s_and_saveexec_b64 s[0:1], vcc
	s_xor_b64 s[0:1], exec, s[0:1]
	s_cbranch_execz .LBB0_1547
	v_mov_b32_e32 v0, s74
	v_add_co_u32_e32 v2, vcc, 0x3000, v0
	v_mov_b32_e32 v0, s75
	s_nop 0
	v_addc_co_u32_e32 v3, vcc, 0, v0, vcc
	flat_load_dword v0, v[2:3] offset:1280 sc1
	s_add_u32 s6, s74, 0x3500
	s_addc_u32 s7, s75, 0
	s_waitcnt vmcnt(0) lgkmcnt(0)
	v_cmp_eq_u32_e32 vcc, v0, v1
	s_and_saveexec_b64 s[4:5], vcc
	s_cbranch_execz .LBB0_1546
	s_mov_b32 s24, 1
	s_mov_b64 s[8:9], 0
	s_branch .LBB0_1538

; DI unsigned xb_ld(unsigned* p) { return __hip_atomic_load(p, __ATOMIC_RELAXED, __HIP_MEMORY_SCOPE_AGENT); }
; DI unsigned xb_add(unsigned* p, unsigned v) { return __hip_atomic_fetch_add(p, v, __ATOMIC_RELAXED, __HIP_MEMORY_SCOPE_AGENT); }
; #define XB_SPIN(cond, bar) do { unsigned _sp = 0; while (cond) { __builtin_amdgcn_s_sleep(1); \
;     if ((++_sp & 255u) == 0u) { if (xb_ld(&(bar)[XB_TMO])) break; if (_sp > XB_SPIN_CAP) { atomicAdd(&(bar)[XB_TMO], 1u); break; } } } } while (0)
; DI void xcd_barrier(int wv, unsigned* bar0, volatile LAS unsigned* st) {
;     ...
;         const unsigned old = xb_add(&bar[XB_XSUB(x)], 1u);
;         const unsigned gen = old / nloc;
;         if (old + 1u == (gen + 1u) * nloc) {
;             __builtin_amdgcn_fence(__ATOMIC_RELEASE, "agent");
;             asm volatile("s_waitcnt vmcnt(0)" ::: "memory");
;             const unsigned og = xb_add(&bar[XB_TOP], 1u);
;             const unsigned tg = og / nx;
;             if (og + 1u == (tg + 1u) * nx) xb_add(&bar[XB_TOPGEN], 1u);
;             else XB_SPIN(xb_ld(&bar[XB_TOPGEN]) == tg, bar);
;             __builtin_amdgcn_fence(__ATOMIC_ACQUIRE, "agent");
;             xb_add(&bar[XB_XGEN(x)], 1u);
;             asm volatile("s_waitcnt vmcnt(0)" ::: "memory");
;         } else {
;             XB_SPIN(xb_ld(&bar[XB_XGEN(x)]) == gen, bar);
;             __builtin_amdgcn_fence(__ATOMIC_ACQUIRE, "agent");
;             asm volatile("s_waitcnt vmcnt(0)" ::: "memory");
;         }
.LBB0_1593:
	s_lshl_b32 s0, s34, 8
	s_add_u32 s23, s52, s0
	s_addc_u32 s22, s53, 0
	v_mov_b32_e32 v1, s23
	v_add_co_u32_e32 v4, vcc, 0x1000, v1
	v_mov_b32_e32 v1, s22
	s_nop 0
	v_addc_co_u32_e32 v5, vcc, 0, v1, vcc
	v_mov_b32_e32 v1, 1
	flat_atomic_add v3, v[4:5], v1 offset:1024 sc0
	v_cvt_f32_u32_e32 v1, v2
	v_sub_u32_e32 v4, 0, v2
	v_rcp_iflag_f32_e32 v1, v1
	s_nop 0
	v_mul_f32_e32 v1, 0x4f7ffffe, v1
	v_cvt_u32_f32_e32 v1, v1
	v_mul_lo_u32 v4, v4, v1
	v_mul_hi_u32 v4, v1, v4
	v_add_u32_e32 v1, v1, v4
	s_waitcnt vmcnt(0) lgkmcnt(0)
	v_mul_hi_u32 v1, v3, v1
	v_mul_lo_u32 v4, v1, v2
	v_sub_u32_e32 v4, v3, v4
	v_cmp_ge_u32_e32 vcc, v4, v2
	v_add_u32_e32 v5, 1, v1
	s_nop 0
	v_cndmask_b32_e32 v1, v1, v5, vcc
	v_sub_u32_e32 v5, v4, v2
	v_cndmask_b32_e32 v4, v4, v5, vcc
	v_cmp_ge_u32_e32 vcc, v4, v2
	v_add_u32_e32 v4, 1, v1
	s_nop 0
	v_cndmask_b32_e32 v1, v1, v4, vcc
	v_add_u32_e32 v4, 1, v3
	v_mad_u64_u32 v[2:3], s[0:1], v2, v1, v[2:3]
	v_cmp_ne_u32_e32 vcc, v4, v2
	s_and_saveexec_b64 s[0:1], vcc
	s_xor_b64 s[0:1], exec, s[0:1]
	s_cbranch_execz .LBB0_1606
	v_mov_b32_e32 v0, s52
	v_add_co_u32_e32 v2, vcc, 0x3000, v0
	v_mov_b32_e32 v0, s53
	s_nop 0
	v_addc_co_u32_e32 v3, vcc, 0, v0, vcc
	flat_load_dword v0, v[2:3] offset:1280 sc1
	s_add_u32 s6, s52, 0x3500
	s_addc_u32 s7, s53, 0
	s_waitcnt vmcnt(0) lgkmcnt(0)
	v_cmp_eq_u32_e32 vcc, v0, v1
	s_and_saveexec_b64 s[4:5], vcc
	s_cbranch_execz .LBB0_1605
	s_mov_b32 s24, 1
	s_mov_b64 s[8:9], 0
	s_branch .LBB0_1597
